# attention unit prologue: kmax load and tile-1/2 LDS-DMA hoisted above the Q-DMA wait (own-queue copy)
# baseline (speedup 1.0000x reference)
.LBB0_297:
	s_cmpk_gt_i32 s46, 0x4f
	v_readlane_b32 s4, v245, 14
	s_cselect_b64 s[2:3], -1, 0
	s_cmp_lt_u32 s46, s4
	s_cselect_b64 s[4:5], -1, 0
	s_and_b64 s[2:3], s[2:3], s[4:5]
	s_andn2_b64 vcc, exec, s[2:3]
	s_mov_b64 s[2:3], -1
	s_cbranch_vccz .LBB0_352
	s_cmpk_gt_i32 s46, 0x4f
	v_readlane_b32 s2, v245, 13
	s_cselect_b32 s2, s2, 0
	s_sub_i32 s2, s46, s2
	s_bfe_u32 s4, s2, 0x30001
	s_and_b32 s3, s2, 1
	s_xor_b32 s5, s4, 7
	s_or_b32 s4, s4, 8
	s_cmp_eq_u32 s3, 0
	s_cselect_b32 s3, s4, s5
	s_mov_b64 s[4:5], s[0:1]
	s_mov_b64 s[12:13], s[0:1]
	s_load_dwordx2 s[4:5], s[4:5], 0x80
	s_load_dwordx2 s[74:75], s[12:13], 0x80
	s_mov_b64 s[12:13], s[0:1]
	s_ashr_i32 s2, s2, 4
	s_load_dwordx2 s[78:79], s[12:13], 0x28
	s_sub_i32 s12, 8, s2
	v_cvt_f32_i32_e32 v0, s12
	v_mov_b32_e32 v19, v220
	v_readlane_b32 s13, v245, 17
	v_exp_f32_e64 v0, -v0
	s_sub_i32 s55, 7, s2
	s_lshl_b32 s76, s55, 6
	v_ashrrev_i32_e32 v2, 5, v19
	v_readfirstlane_b32 s12, v0
	v_ashrrev_i32_e32 v0, 3, v19
	v_add_u32_e32 v0, s13, v0
	v_mul_lo_u32 v3, v0, s88
	v_lshrrev_b32_e32 v0, 1, v0
	s_add_i32 s13, s76, 0x200
	v_xor_b32_e32 v0, v0, v19
	v_add_u32_e32 v3, s13, v3
	v_lshlrev_b32_e32 v0, 3, v0
	v_readlane_b32 s13, v245, 16
	v_and_or_b32 v0, v0, 56, v3
	v_lshlrev_b32_e32 v4, 3, v19
	v_lshl_add_u32 v3, v2, 3, s13
	v_readlane_b32 s13, v245, 18
	s_add_i32 s13, s13, s76
	v_and_b32_e32 v20, 24, v4
	v_or_b32_e32 v9, s13, v20
	v_readlane_b32 s13, v245, 19
	s_waitcnt lgkmcnt(0)
	s_add_u32 s4, s4, s13
	s_addc_u32 s5, s5, 0
	s_add_u32 s60, s4, 0x13200000
	s_addc_u32 s61, s5, 0
	s_mul_i32 s4, s3, 0xc0000
	s_add_u32 s80, s60, s4
	v_lshlrev_b32_e32 v0, 1, v0
	s_addc_u32 s81, s61, 0
	s_movk_i32 s4, 0xfc00
	v_lshl_add_u64 v[4:5], s[80:81], 0, v[0:1]
	s_mov_b32 s5, -1
	v_lshl_add_u64 v[6:7], v[4:5], 0, s[4:5]
	v_readlane_b32 s5, v245, 22
	s_mov_b32 s4, m0
	s_mov_b32 m0, s5
	s_nop 0
	global_load_lds_dwordx4 v[6:7], off
	s_mov_b32 m0, s4
	s_mov_b64 s[4:5], 0x2fc00
	v_bfe_u32 v8, v19, 2, 3
	v_lshl_add_u64 v[6:7], v[4:5], 0, s[4:5]
	v_readlane_b32 s5, v245, 20
	s_mov_b32 s4, m0
	s_mov_b32 m0, s5
	s_nop 0
	global_load_lds_dwordx4 v[6:7], off
	s_mov_b32 m0, s4
	s_mov_b64 s[4:5], 0x5fc00
	v_or_b32_e32 v3, v3, v8
	v_lshl_add_u64 v[6:7], v[4:5], 0, s[4:5]
	v_readlane_b32 s5, v245, 21
	s_mov_b32 s4, m0
	s_mov_b32 m0, s5
	s_nop 0
	global_load_lds_dwordx4 v[6:7], off
	s_mov_b32 m0, s4
	s_mov_b64 s[4:5], 0x8fc00
	v_mul_lo_u32 v3, v3, s88
	v_lshl_add_u64 v[6:7], v[4:5], 0, s[4:5]
	v_readlane_b32 s5, v245, 23
	s_mov_b32 s4, m0
	s_mov_b32 m0, s5
	s_nop 0
	global_load_lds_dwordx4 v[6:7], off
	s_mov_b32 m0, s4
	v_add_lshl_u32 v170, v9, v3, 1
	s_mov_b32 s4, m0
	s_mov_b32 m0, s64
	s_nop 0
	global_load_lds_dwordx4 v[4:5], off
	s_mov_b32 m0, s4
	v_mov_b32_e32 v171, v1
	v_lshl_add_u64 v[4:5], s[80:81], 0, v[170:171]
	v_readlane_b32 s5, v245, 24
	s_mov_b32 s4, m0
	s_mov_b32 m0, s5
	s_nop 0
	global_load_lds_dwordx4 v[4:5], off
	s_mov_b32 m0, s4
	v_lshlrev_b32_e32 v4, 2, v19
	v_readlane_b32 s4, v245, 25
	v_and_b32_e32 v9, 4, v4
	v_bitop3_b32 v4, v4, v8, 4 bitop3:0x6c
	v_lshl_add_u32 v3, v19, 6, s4
	v_and_b32_e32 v3, 0xffffff80, v3
	v_add_u32_e32 v3, s63, v3
	v_lshl_add_u32 v4, v4, 4, v3
	s_ashr_i32 s101, s2, 31
	s_mov_b32 s100, s2
	s_lshl_b64 s[100:101], s[100:101], 2
	s_sub_u32 s100, s7, s100
	s_subb_u32 s101, s33, s101
	v_mov_b32_e32 v248, 0
	global_load_dword v249, v248, s[100:101] offset:28 sc1
	s_add_u32 s100, s80, 0x30000
	s_addc_u32 s101, s81, 0
	v_lshl_add_u64 v[250:251], s[100:101], 0, v[0:1]
	v_lshl_add_u64 v[252:253], s[100:101], 0, v[170:171]
	v_readlane_b32 s98, v245, 27
	s_mov_b32 s99, m0
	s_mov_b32 m0, s98
	s_nop 0
	global_load_lds_dwordx4 v[250:251], off
	v_readlane_b32 s98, v245, 28
	s_nop 0
	s_mov_b32 m0, s98
	s_nop 0
	global_load_lds_dwordx4 v[252:253], off
	s_add_u32 s100, s80, 0x60000
	s_addc_u32 s101, s81, 0
	v_lshl_add_u64 v[250:251], s[100:101], 0, v[0:1]
	v_lshl_add_u64 v[252:253], s[100:101], 0, v[170:171]
	v_readlane_b32 s98, v245, 29
	s_nop 0
	s_mov_b32 m0, s98
	s_nop 0
	global_load_lds_dwordx4 v[250:251], off
	v_readlane_b32 s98, v245, 30
	s_nop 0
	s_mov_b32 m0, s98
	s_nop 0
	global_load_lds_dwordx4 v[252:253], off
	s_mov_b32 m0, s99
	s_waitcnt vmcnt(5)
	s_barrier
	ds_read_b128 v[4:7], v4
	v_cmp_eq_u32_e32 vcc, 0, v19
	s_waitcnt lgkmcnt(0)
	v_lshlrev_b32_e32 v10, 16, v4
	v_and_b32_e32 v4, 0xffff0000, v4
	v_mul_f32_e32 v11, v4, v4
	v_fmac_f32_e32 v11, v10, v10
	v_lshlrev_b32_e32 v4, 16, v5
	v_fmac_f32_e32 v11, v4, v4
	v_and_b32_e32 v4, 0xffff0000, v5
	v_fmac_f32_e32 v11, v4, v4
	v_lshlrev_b32_e32 v4, 16, v6
	v_fmac_f32_e32 v11, v4, v4
	v_and_b32_e32 v4, 0xffff0000, v6
	v_fmac_f32_e32 v11, v4, v4
	v_lshlrev_b32_e32 v4, 16, v7
	v_fmac_f32_e32 v11, v4, v4
	v_and_b32_e32 v4, 0xffff0000, v7
	v_fmac_f32_e32 v11, v4, v4
	v_bitop3_b32 v4, v9, v8, 1 bitop3:0x36
	v_lshl_add_u32 v4, v4, 4, v3
	ds_read_b128 v[4:7], v4
	s_waitcnt lgkmcnt(0)
	v_lshlrev_b32_e32 v10, 16, v4
	v_fmac_f32_e32 v11, v10, v10
	v_and_b32_e32 v4, 0xffff0000, v4
	v_fmac_f32_e32 v11, v4, v4
	v_lshlrev_b32_e32 v4, 16, v5
	v_fmac_f32_e32 v11, v4, v4
	v_and_b32_e32 v4, 0xffff0000, v5
	v_fmac_f32_e32 v11, v4, v4
	v_lshlrev_b32_e32 v4, 16, v6
	v_fmac_f32_e32 v11, v4, v4
	v_and_b32_e32 v4, 0xffff0000, v6
	v_fmac_f32_e32 v11, v4, v4
	v_lshlrev_b32_e32 v4, 16, v7
	v_fmac_f32_e32 v11, v4, v4
	v_and_b32_e32 v4, 0xffff0000, v7
	v_fmac_f32_e32 v11, v4, v4
	v_bitop3_b32 v4, v9, v8, 2 bitop3:0x36
	v_lshl_add_u32 v4, v4, 4, v3
	ds_read_b128 v[4:7], v4
	s_waitcnt lgkmcnt(0)
	v_lshlrev_b32_e32 v10, 16, v4
	v_fmac_f32_e32 v11, v10, v10
	v_and_b32_e32 v4, 0xffff0000, v4
	v_fmac_f32_e32 v11, v4, v4
	v_lshlrev_b32_e32 v4, 16, v5
	v_fmac_f32_e32 v11, v4, v4
	v_and_b32_e32 v4, 0xffff0000, v5
	v_fmac_f32_e32 v11, v4, v4
	v_lshlrev_b32_e32 v4, 16, v6
	v_fmac_f32_e32 v11, v4, v4
	v_and_b32_e32 v4, 0xffff0000, v6
	v_fmac_f32_e32 v11, v4, v4
	v_lshlrev_b32_e32 v4, 16, v7
	v_fmac_f32_e32 v11, v4, v4
	v_and_b32_e32 v4, 0xffff0000, v7
	v_fmac_f32_e32 v11, v4, v4
	v_bitop3_b32 v4, v9, v8, 3 bitop3:0x36
	v_lshl_add_u32 v3, v4, 4, v3
	ds_read_b128 v[4:7], v3
	s_waitcnt lgkmcnt(0)
	v_lshlrev_b32_e32 v3, 16, v4
	v_fmac_f32_e32 v11, v3, v3
	v_and_b32_e32 v3, 0xffff0000, v4
	v_fmac_f32_e32 v11, v3, v3
	v_lshlrev_b32_e32 v3, 16, v5
	v_fmac_f32_e32 v11, v3, v3
	v_and_b32_e32 v3, 0xffff0000, v5
	v_fmac_f32_e32 v11, v3, v3
	v_lshlrev_b32_e32 v3, 16, v6
	v_fmac_f32_e32 v11, v3, v3
	v_and_b32_e32 v3, 0xffff0000, v6
	v_fmac_f32_e32 v11, v3, v3
	v_lshlrev_b32_e32 v3, 16, v7
	v_fmac_f32_e32 v11, v3, v3
	v_and_b32_e32 v3, 0xffff0000, v7
	v_fmac_f32_e32 v11, v3, v3
	ds_bpermute_b32 v3, v221, v11
	s_waitcnt lgkmcnt(0)
	v_max_f32_e32 v3, v3, v3
	v_max_f32_e32 v3, v11, v3
	ds_bpermute_b32 v4, v222, v3
	s_waitcnt lgkmcnt(0)
	v_max_f32_e32 v4, v4, v4
	v_max_f32_e32 v3, v3, v4
	ds_bpermute_b32 v4, v223, v3
	s_waitcnt lgkmcnt(0)
	v_max_f32_e32 v4, v4, v4
	v_max_f32_e32 v3, v3, v4
	ds_bpermute_b32 v4, v224, v3
	s_waitcnt lgkmcnt(0)
	v_max_f32_e32 v4, v4, v4
	v_max_f32_e32 v3, v3, v4
	ds_bpermute_b32 v4, v225, v3
	s_waitcnt lgkmcnt(0)
	v_max_f32_e32 v4, v4, v4
	v_max_f32_e32 v3, v3, v4
	ds_bpermute_b32 v4, v226, v3
	s_and_saveexec_b64 s[4:5], vcc
	s_cbranch_execz .LBB0_300
	s_waitcnt lgkmcnt(0)
	v_max_f32_e32 v4, v4, v4
	v_max_f32_e32 v3, v3, v3
	v_readlane_b32 s13, v245, 26
	v_max_f32_e32 v3, v3, v4
	s_nop 0
	v_mov_b32_e32 v4, s13
	ds_write_b32 v4, v3
.LBB0_300:
	s_or_b64 exec, exec, s[4:5]
	s_lshl_b32 s4, s3, 8
	v_readlane_b32 s5, v245, 15
	s_lshl_b32 s69, s3, 2
	s_ashr_i32 s3, s2, 31
	s_add_i32 s68, s4, s5
	s_lshl_b64 s[2:3], s[2:3], 2
	s_sub_u32 s2, s7, s2
	v_mov_b32_e32 v3, s11
	v_mov_b32_e32 v8, s89
	s_subb_u32 s3, s33, s3
	v_mov_b32_e32 v175, 0
	s_waitcnt lgkmcnt(0)
	s_barrier
	ds_read_b128 v[4:7], v3
	ds_read_b128 v[8:11], v8
	v_and_b32_e32 v185, 31, v19
	v_lshrrev_b32_e32 v3, 1, v19
	v_lshlrev_b32_e32 v172, 2, v2
	v_lshlrev_b32_e32 v12, 7, v185
	v_bitop3_b32 v2, v3, v2, 7 bitop3:0x6c
	v_mul_f32_e32 v18, s12, v235
	v_lshl_add_u32 v186, v2, 4, v12
	v_or_b32_e32 v2, s68, v185
	v_cvt_f32_i32_e32 v3, v172
	v_mul_f32_e32 v173, 0x42800000, v18
	s_mov_b32 s56, 0x41600000
	v_cvt_f32_u32_e32 v2, v2
	v_div_scale_f32 v58, s[2:3], v173, v173, s56
	v_cvt_f32_u32_e32 v13, s4
	v_rcp_f32_e32 v60, v58
	s_waitcnt lgkmcnt(1)
	v_max_f32_e32 v5, v5, v5
	v_max_f32_e32 v4, v4, v4
	v_sub_f32_e32 v187, v3, v2
	v_max_f32_e32 v2, v4, v5
	v_max3_f32 v2, v2, v6, v7
	v_fma_f32 v3, -v58, v60, 1.0
	v_add_f32_e32 v176, v187, v13
	s_waitcnt lgkmcnt(0)
	v_max3_f32 v23, v2, v8, v9
	v_fmac_f32_e32 v60, v3, v60
	v_pk_add_f32 v[2:3], v[176:177], s[14:15] op_sel_hi:[0,1]
	v_max3_f32 v23, v23, v10, v11
	v_and_b32_e32 v24, 0x7fffffff, v2
	s_mov_b32 s2, 0xf800000
	v_and_b32_e32 v25, 0x7fffffff, v3
	v_pk_add_f32 v[12:13], v[176:177], s[22:23] op_sel_hi:[0,1]
	v_pk_add_f32 v[14:15], v[176:177], s[24:25] op_sel_hi:[0,1]
	v_pk_add_f32 v[16:17], v[176:177], s[26:27] op_sel_hi:[0,1]
	v_add_f32_e32 v26, 1.0, v176
	v_and_b32_e32 v11, 0x7fffffff, v13
	v_and_b32_e32 v10, 0x7fffffff, v12
	v_and_b32_e32 v13, 0x7fffffff, v15
	v_and_b32_e32 v12, 0x7fffffff, v14
	v_and_b32_e32 v15, 0x7fffffff, v17
	v_and_b32_e32 v14, 0x7fffffff, v16
	v_and_b32_e32 v22, 0x7fffffff, v176
	v_pk_mul_f32 v[16:17], v[14:15], v[18:19] op_sel_hi:[1,0] neg_lo:[0,1] neg_hi:[0,1]
	v_pk_add_f32 v[8:9], v[176:177], s[20:21] op_sel_hi:[0,1]
	v_and_b32_e32 v9, 0x7fffffff, v9
	v_and_b32_e32 v8, 0x7fffffff, v8
	v_readlane_b32 s55, v245, 28
	v_pk_add_f32 v[4:5], v[176:177], s[16:17] op_sel_hi:[0,1]
	v_pk_add_f32 v[6:7], v[176:177], s[18:19] op_sel_hi:[0,1]
	v_xor_b32_e32 v188, 32, v186
	v_and_b32_e32 v5, 0x7fffffff, v5
	v_and_b32_e32 v4, 0x7fffffff, v4
	v_and_b32_e32 v7, 0x7fffffff, v7
	v_and_b32_e32 v6, 0x7fffffff, v6
	v_add_u32_e32 v61, 0, v188
	v_add_u32_e32 v189, s52, v186
	v_add_u32_e32 v192, s52, v188
	v_div_scale_f32 v59, s[4:5], s56, v173, s56
	v_pk_add_f32 v[42:43], v[176:177], s[28:29] op_sel_hi:[0,1]
	v_pk_add_f32 v[44:45], v[176:177], s[30:31] op_sel_hi:[0,1]
	v_pk_add_f32 v[46:47], v[176:177], s[34:35] op_sel_hi:[0,1]
	v_pk_add_f32 v[48:49], v[176:177], s[36:37] op_sel_hi:[0,1]
	v_pk_add_f32 v[50:51], v[176:177], s[38:39] op_sel_hi:[0,1]
	v_pk_add_f32 v[52:53], v[176:177], s[40:41] op_sel_hi:[0,1]
	v_pk_add_f32 v[54:55], v[176:177], s[42:43] op_sel_hi:[0,1]
	v_pk_add_f32 v[56:57], v[176:177], s[44:45] op_sel_hi:[0,1]
	v_and_b32_e32 v57, 0x7fffffff, v57
	v_and_b32_e32 v56, 0x7fffffff, v56
	v_and_b32_e32 v55, 0x7fffffff, v55
	v_and_b32_e32 v54, 0x7fffffff, v54
	v_and_b32_e32 v53, 0x7fffffff, v53
	v_and_b32_e32 v52, 0x7fffffff, v52
	v_and_b32_e32 v51, 0x7fffffff, v51
	v_and_b32_e32 v50, 0x7fffffff, v50
	v_and_b32_e32 v49, 0x7fffffff, v49
	v_and_b32_e32 v48, 0x7fffffff, v48
	v_and_b32_e32 v47, 0x7fffffff, v47
	v_and_b32_e32 v46, 0x7fffffff, v46
	v_and_b32_e32 v45, 0x7fffffff, v45
	s_waitcnt vmcnt(4)
	v_mul_f32_e32 v2, v23, v249
	v_mul_f32_e32 v3, 0x4f800000, v2
	v_cmp_gt_f32_e32 vcc, s2, v2
	v_and_b32_e32 v23, 0x7fffffff, v26
	v_and_b32_e32 v44, 0x7fffffff, v44
	v_cndmask_b32_e32 v21, v2, v3, vcc
	v_sqrt_f32_e32 v27, v21
	v_pk_mul_f32 v[2:3], v[22:23], v[18:19] op_sel_hi:[1,0] neg_lo:[0,1] neg_hi:[0,1]
	v_and_b32_e32 v43, 0x7fffffff, v43
	v_and_b32_e32 v42, 0x7fffffff, v42
	v_add_u32_e32 v14, -1, v27
	v_add_u32_e32 v15, 1, v27
	v_fma_f32 v22, -v14, v27, v21
	v_fma_f32 v23, -v15, v27, v21
	v_cmp_ge_f32_e64 s[2:3], 0, v22
	v_pk_mul_f32 v[96:97], v[42:43], v[18:19] op_sel_hi:[1,0] neg_lo:[0,1] neg_hi:[0,1]
	v_pk_mul_f32 v[94:95], v[44:45], v[18:19] op_sel_hi:[1,0] neg_lo:[0,1] neg_hi:[0,1]
	v_cndmask_b32_e64 v14, v27, v14, s[2:3]
	v_cmp_lt_f32_e64 s[2:3], 0, v23
	v_pk_mul_f32 v[92:93], v[46:47], v[18:19] op_sel_hi:[1,0] neg_lo:[0,1] neg_hi:[0,1]
	v_pk_mul_f32 v[90:91], v[48:49], v[18:19] op_sel_hi:[1,0] neg_lo:[0,1] neg_hi:[0,1]
	v_cndmask_b32_e64 v14, v14, v15, s[2:3]
	v_mul_f32_e32 v15, 0x37800000, v14
	v_cndmask_b32_e32 v14, v14, v15, vcc
	v_cmp_class_f32_e32 vcc, v21, v232
	v_pk_mul_f32 v[88:89], v[50:51], v[18:19] op_sel_hi:[1,0] neg_lo:[0,1] neg_hi:[0,1]
	v_pk_mul_f32 v[86:87], v[52:53], v[18:19] op_sel_hi:[1,0] neg_lo:[0,1] neg_hi:[0,1]
	v_cndmask_b32_e32 v14, v14, v21, vcc
	v_mul_f32_e32 v21, 0x3f828f5c, v14
	v_fmaak_f32 v22, 2.0, v21, 0x42000000
	v_div_scale_f32 v23, s[2:3], v18, v18, v22
	v_rcp_f32_e32 v26, v23
	v_pk_mul_f32 v[14:15], v[12:13], v[18:19] op_sel_hi:[1,0] neg_lo:[0,1] neg_hi:[0,1]
	v_div_scale_f32 v12, vcc, v22, v18, v22
	v_fma_f32 v13, -v23, v26, 1.0
	v_fmac_f32_e32 v26, v13, v26
	v_mul_f32_e32 v13, v12, v26
	v_fma_f32 v27, -v23, v13, v12
	v_fmac_f32_e32 v13, v27, v26
	v_fma_f32 v12, -v23, v13, v12
	v_div_fmas_f32 v12, v12, v26, v13
	v_div_fixup_f32 v22, v12, v18, v22
	v_cvt_i32_f32_e32 v23, v22
	v_cmp_gt_f32_e32 vcc, s90, v22
	v_pk_mul_f32 v[12:13], v[10:11], v[18:19] op_sel_hi:[1,0] neg_lo:[0,1] neg_hi:[0,1]
	v_pk_mul_f32 v[10:11], v[8:9], v[18:19] op_sel_hi:[1,0] neg_lo:[0,1] neg_hi:[0,1]
	v_readfirstlane_b32 s2, v23
	s_add_i32 s12, s2, 1
	s_and_b64 s[2:3], vcc, exec
	s_cselect_b32 s2, s12, 0x2000
	s_add_i32 s12, s2, 62
	s_add_i32 s2, s2, -2
	s_ashr_i32 s12, s12, 6
	s_ashr_i32 s2, s2, 6
	s_xor_b32 s3, s69, 60
	s_min_i32 s77, s69, s12
	s_add_i32 s2, s2, 1
	s_min_i32 s2, s3, s2
	s_add_i32 s82, s77, 4
	s_add_u32 s12, s80, 0x30000
	s_addc_u32 s13, s81, 0
	s_add_u32 s12, s80, 0x60000
	v_readlane_b32 s13, v245, 27
	s_addc_u32 s13, s81, 0
	v_add_u32_e32 v26, 0, v186
	v_readlane_b32 s12, v245, 29
	v_readlane_b32 s12, v245, 30
	v_pk_mul_f32 v[8:9], v[6:7], v[18:19] op_sel_hi:[1,0] neg_lo:[0,1] neg_hi:[0,1]
	v_pk_mul_f32 v[6:7], v[4:5], v[18:19] op_sel_hi:[1,0] neg_lo:[0,1] neg_hi:[0,1]
	v_pk_mul_f32 v[4:5], v[24:25], v[18:19] op_sel_hi:[1,0] neg_lo:[0,1] neg_hi:[0,1]
	ds_read_b128 v[22:25], v26
	ds_read_b128 v[26:29], v26 offset:4096
	ds_read_b128 v[30:33], v61
	ds_read_b128 v[34:37], v189
	ds_read_b128 v[38:41], v192
	s_waitcnt lgkmcnt(1)
	v_mfma_f32_32x32x16_bf16 v[98:113], v[22:25], v[34:37], v[2:17]
	v_mul_f32_e32 v22, v59, v60
	v_fma_f32 v23, -v58, v22, v59
	v_fmac_f32_e32 v22, v23, v60
	v_mul_f32_e64 v84, v54, -v18
	v_mul_f32_e64 v85, v55, -v18
	v_pk_mul_f32 v[82:83], v[56:57], v[18:19] op_sel_hi:[1,0] neg_lo:[0,1] neg_hi:[0,1]
	v_fma_f32 v23, -v58, v22, v59
	s_mov_b64 vcc, s[4:5]
	v_mfma_f32_32x32x16_bf16 v[82:97], v[26:29], v[34:37], v[82:97]
	v_div_fmas_f32 v26, v23, v60, v22
	ds_read_b128 v[22:25], v61 offset:4096
	v_div_fixup_f32 v26, v26, v173, s56
	v_cmp_gt_f32_e32 vcc, s24, v21
	s_add_i32 s83, s82, s2
	s_cmp_lt_i32 s83, 1
	v_cndmask_b32_e32 v21, 0, v26, vcc
	s_waitcnt lgkmcnt(1)
	v_mfma_f32_32x32x16_bf16 v[98:113], v[30:33], v[38:41], v[98:113]
	v_min_f32_e32 v21, 0x42800000, v21
	s_nop 0
	v_readfirstlane_b32 s3, v21
	s_waitcnt lgkmcnt(0)
	v_mfma_f32_32x32x16_bf16 v[82:97], v[22:25], v[38:41], v[82:97]
	s_cbranch_scc1 .LBB0_350
	v_lshrrev_b32_e32 v21, 2, v19
	v_lshlrev_b32_e32 v19, 1, v19
	v_cvt_i32_f32_e32 v193, s3
	v_and_or_b32 v21, v21, 3, v172
	v_and_or_b32 v19, v19, 32, v20
	v_lshl_or_b32 v19, v21, 6, v19
	v_mov_b32_e32 v50, v1
	v_mov_b32_e32 v51, v1
	v_mov_b32_e32 v64, v1
	v_mov_b32_e32 v65, v1
	v_xor_b32_e32 v178, 0x80000000, v18
	v_add_u32_e32 v195, 0x2000, v19
	v_mul_f32_e32 v196, 0x42000000, v18
	v_mul_f32_e32 v197, 0xc2000000, v18
	s_add_i32 s86, s2, s77
	v_mov_b32_e32 v52, v1
	v_mov_b32_e32 v53, v1
	v_mov_b32_e32 v54, v1
	v_mov_b32_e32 v55, v1
	v_mov_b32_e32 v56, v1
	v_mov_b32_e32 v57, v1
	v_mov_b32_e32 v58, v1
	v_mov_b32_e32 v59, v1
	v_mov_b32_e32 v60, v1
	v_mov_b32_e32 v61, v1
	v_mov_b32_e32 v62, v1
	v_mov_b32_e32 v63, v1
	v_mov_b64_e32 v[18:19], v[50:51]
	v_mov_b64_e32 v[80:81], v[64:65]
	v_mov_b64_e32 v[34:35], v[50:51]
	v_mov_b32_e32 v180, v178
	v_mov_b32_e32 v181, v178
	v_xor_b32_e32 v194, 64, v186
	s_sub_i32 s84, s69, s77
	s_or_b32 s85, s69, 3
	v_xor_b32_e32 v198, 0x60, v186
	s_add_i32 s86, s86, 4
	s_add_i32 s87, s77, 3
	s_mov_b32 s88, 0
	v_mov_b32_e32 v174, v1
	v_mov_b32_e32 v175, v1
	v_mov_b32_e32 v182, 0
	s_mov_b32 s89, s69
	v_mov_b64_e32 v[20:21], v[52:53]
	v_mov_b64_e32 v[22:23], v[54:55]
	v_mov_b64_e32 v[24:25], v[56:57]
	v_mov_b64_e32 v[26:27], v[58:59]
	v_mov_b64_e32 v[28:29], v[60:61]
	v_mov_b64_e32 v[30:31], v[62:63]
	v_mov_b64_e32 v[32:33], v[64:65]
	v_mov_b64_e32 v[78:79], v[62:63]
	v_mov_b64_e32 v[76:77], v[60:61]
	v_mov_b64_e32 v[74:75], v[58:59]
	v_mov_b64_e32 v[72:73], v[56:57]
	v_mov_b64_e32 v[70:71], v[54:55]
	v_mov_b64_e32 v[68:69], v[52:53]
	v_mov_b64_e32 v[66:67], v[50:51]
	v_mov_b64_e32 v[36:37], v[52:53]
	v_mov_b64_e32 v[38:39], v[54:55]
	v_mov_b64_e32 v[40:41], v[56:57]
	v_mov_b64_e32 v[42:43], v[58:59]
	v_mov_b64_e32 v[44:45], v[60:61]
	v_mov_b64_e32 v[46:47], v[62:63]
	v_mov_b64_e32 v[48:49], v[64:65]
	s_mov_b32 s90, 0
	s_add_i32 s2, s90, 2
	s_cmp_ge_i32 s2, s83
	s_mov_b64 s[2:3], -1
	s_cbranch_scc0 .LBB0_303

.LBB0_310:
	s_cmp_lt_i32 s90, s82
	s_cselect_b64 s[4:5], -1, 0
	s_add_i32 s12, s88, 0
	v_add_u32_e32 v114, s12, v194
	ds_read_b128 v[158:161], v114
	ds_read_b128 v[150:153], v114 offset:4096
	v_add_u32_e32 v114, s12, v198
	ds_read_b128 v[154:157], v114
	ds_read_b128 v[146:149], v114 offset:4096
	v_add_u32_e32 v114, s52, v194
	v_add_u32_e32 v115, s52, v198
	ds_read_b128 v[166:169], v114
	ds_read_b128 v[162:165], v115
	s_cmp_lt_u32 s90, 4
	s_cselect_b64 s[2:3], -1, 0
	s_mov_b64 s[12:13], -1
	s_and_b64 vcc, exec, s[2:3]
	s_cbranch_vccnz .LBB0_312
	v_cndmask_b32_e64 v114, v197, v196, s[4:5]
	v_pk_add_f32 v[128:129], v[114:115], v[16:17] op_sel_hi:[0,1]
	v_pk_add_f32 v[126:127], v[114:115], v[14:15] op_sel_hi:[0,1]
	v_pk_add_f32 v[124:125], v[114:115], v[12:13] op_sel_hi:[0,1]
	v_pk_add_f32 v[122:123], v[114:115], v[10:11] op_sel_hi:[0,1]
	v_pk_add_f32 v[120:121], v[114:115], v[8:9] op_sel_hi:[0,1]
	v_pk_add_f32 v[118:119], v[114:115], v[6:7] op_sel_hi:[0,1]
	v_pk_add_f32 v[116:117], v[114:115], v[4:5] op_sel_hi:[0,1]
	v_pk_add_f32 v[114:115], v[114:115], v[2:3] op_sel_hi:[0,1]
	s_mov_b64 s[12:13], 0
.LBB0_312:
	s_andn2_b64 vcc, exec, s[12:13]
	s_cbranch_vccnz .LBB0_314
	v_pk_add_f32 v[114:115], v[176:177], s[28:29] op_sel_hi:[0,1]
	v_pk_add_f32 v[116:117], v[176:177], s[30:31] op_sel_hi:[0,1]
	v_pk_add_f32 v[118:119], v[176:177], s[34:35] op_sel_hi:[0,1]
	v_pk_add_f32 v[120:121], v[176:177], s[36:37] op_sel_hi:[0,1]
	v_pk_add_f32 v[122:123], v[176:177], s[38:39] op_sel_hi:[0,1]
	v_pk_add_f32 v[124:125], v[176:177], s[40:41] op_sel_hi:[0,1]
	v_pk_add_f32 v[126:127], v[176:177], s[42:43] op_sel_hi:[0,1]
	v_pk_add_f32 v[128:129], v[176:177], s[44:45] op_sel_hi:[0,1]
	v_and_b32_e32 v131, 0x7fffffff, v129
	v_and_b32_e32 v130, 0x7fffffff, v128
	v_and_b32_e32 v133, 0x7fffffff, v127
	v_and_b32_e32 v132, 0x7fffffff, v126
	v_and_b32_e32 v135, 0x7fffffff, v125
	v_and_b32_e32 v134, 0x7fffffff, v124
	v_and_b32_e32 v137, 0x7fffffff, v123
	v_and_b32_e32 v136, 0x7fffffff, v122
	v_and_b32_e32 v121, 0x7fffffff, v121
	v_and_b32_e32 v120, 0x7fffffff, v120
	v_and_b32_e32 v119, 0x7fffffff, v119
	v_and_b32_e32 v118, 0x7fffffff, v118
	v_and_b32_e32 v117, 0x7fffffff, v117
	v_and_b32_e32 v116, 0x7fffffff, v116
	v_and_b32_e32 v115, 0x7fffffff, v115
	v_and_b32_e32 v114, 0x7fffffff, v114
	v_mov_b32_e32 v179, v178
	v_pk_fma_f32 v[128:129], v[114:115], v[178:179], v[182:183] op_sel_hi:[1,1,0] neg_lo:[0,0,1] neg_hi:[0,0,1]
	v_pk_fma_f32 v[126:127], v[116:117], v[178:179], v[182:183] op_sel_hi:[1,1,0] neg_lo:[0,0,1] neg_hi:[0,0,1]
	v_pk_fma_f32 v[124:125], v[118:119], v[178:179], v[182:183] op_sel_hi:[1,1,0] neg_lo:[0,0,1] neg_hi:[0,0,1]
	v_pk_fma_f32 v[122:123], v[120:121], v[178:179], v[182:183] op_sel_hi:[1,1,0] neg_lo:[0,0,1] neg_hi:[0,0,1]
	v_pk_fma_f32 v[120:121], v[136:137], v[178:179], v[182:183] op_sel_hi:[1,1,0] neg_lo:[0,0,1] neg_hi:[0,0,1]
	v_pk_fma_f32 v[118:119], v[134:135], v[178:179], v[182:183] op_sel_hi:[1,1,0] neg_lo:[0,0,1] neg_hi:[0,0,1]
	v_pk_fma_f32 v[116:117], v[132:133], v[178:179], v[182:183] op_sel_hi:[1,1,0] neg_lo:[0,0,1] neg_hi:[0,0,1]
	v_pk_fma_f32 v[114:115], v[130:131], v[180:181], v[182:183] op_sel_hi:[1,1,0] neg_lo:[0,0,1] neg_hi:[0,0,1]

.LBB0_319:
	s_and_b64 vcc, exec, s[80:81]
	v_add_u32_e32 v199, s88, v195
	s_cbranch_vccz .LBB0_321
	ds_read_b64_tr_b16 v[146:147], v199 offset:0
	ds_read_b64_tr_b16 v[148:149], v199 offset:0x200
	ds_read_b64_tr_b16 v[150:151], v199 offset:0x400
	ds_read_b64_tr_b16 v[152:153], v199 offset:0x600
	ds_read_b64_tr_b16 v[154:155], v199 offset:0x800
	ds_read_b64_tr_b16 v[156:157], v199 offset:0xa00
	ds_read_b64_tr_b16 v[158:159], v199 offset:0xc00
	ds_read_b64_tr_b16 v[160:161], v199 offset:0xe00
	ds_read_b64_tr_b16 v[162:163], v199 offset:0x1000
	ds_read_b64_tr_b16 v[164:165], v199 offset:0x1200
	ds_read_b64_tr_b16 v[166:167], v199 offset:0x1400
	ds_read_b64_tr_b16 v[168:169], v199 offset:0x1600
	ds_read_b64_tr_b16 v[200:201], v199 offset:0x1800
	ds_read_b64_tr_b16 v[202:203], v199 offset:0x1a00
	ds_read_b64_tr_b16 v[204:205], v199 offset:0x1c00
	ds_read_b64_tr_b16 v[206:207], v199 offset:0x1e00
	v_exp_f32_e32 v98, v98
	v_exp_f32_e32 v99, v99
	v_exp_f32_e32 v100, v100
	v_exp_f32_e32 v101, v101
	v_exp_f32_e32 v102, v102
	v_exp_f32_e32 v103, v103
	v_exp_f32_e32 v104, v104
	v_exp_f32_e32 v105, v105
	v_exp_f32_e32 v106, v106
	v_exp_f32_e32 v107, v107
	v_exp_f32_e32 v108, v108
	v_exp_f32_e32 v109, v109
	v_exp_f32_e32 v110, v110
	v_exp_f32_e32 v111, v111
	v_exp_f32_e32 v112, v112
	v_exp_f32_e32 v113, v113
	v_cvt_pk_bf16_f32 v208, v98, v99
	v_cvt_pk_bf16_f32 v209, v100, v101
	v_cvt_pk_bf16_f32 v210, v102, v103
	v_cvt_pk_bf16_f32 v211, v104, v105
	v_cvt_pk_bf16_f32 v212, v106, v107
	v_cvt_pk_bf16_f32 v213, v108, v109
	v_cvt_pk_bf16_f32 v214, v110, v111
	v_cvt_pk_bf16_f32 v215, v112, v113
	s_waitcnt lgkmcnt(0)
	s_nop 0
	v_mfma_f32_32x32x16_bf16 v[50:65], v[146:149], v[208:211], v[50:65]
	v_exp_f32_e32 v82, v82
	v_exp_f32_e32 v83, v83
	v_exp_f32_e32 v84, v84
	v_exp_f32_e32 v85, v85
	v_mfma_f32_32x32x16_bf16 v[18:33], v[162:165], v[208:211], v[18:33]
	v_exp_f32_e32 v86, v86
	v_exp_f32_e32 v87, v87
	v_exp_f32_e32 v88, v88
	v_exp_f32_e32 v89, v89
	v_mfma_f32_32x32x16_bf16 v[50:65], v[150:153], v[212:215], v[50:65]
	v_exp_f32_e32 v90, v90
	v_exp_f32_e32 v91, v91
	v_exp_f32_e32 v92, v92
	v_exp_f32_e32 v93, v93
	v_mfma_f32_32x32x16_bf16 v[18:33], v[166:169], v[212:215], v[18:33]
	v_exp_f32_e32 v94, v94
	v_exp_f32_e32 v95, v95
	v_exp_f32_e32 v96, v96
	v_exp_f32_e32 v97, v97
	v_cvt_pk_bf16_f32 v146, v82, v83
	v_cvt_pk_bf16_f32 v147, v84, v85
	v_cvt_pk_bf16_f32 v148, v86, v87
	v_cvt_pk_bf16_f32 v149, v88, v89
	v_cvt_pk_bf16_f32 v150, v90, v91
	v_cvt_pk_bf16_f32 v151, v92, v93
	v_cvt_pk_bf16_f32 v152, v94, v95
	v_cvt_pk_bf16_f32 v153, v96, v97
	s_nop 0
	v_mfma_f32_32x32x16_bf16 v[50:65], v[154:157], v[146:149], v[50:65]
	v_add_f32_e64 v154, v98, v100
	v_add_f32_e64 v155, v99, v101
	v_add_f32_e64 v156, v102, v104
	v_add_f32_e64 v157, v103, v105
	v_add_f32_e64 v162, v106, v108
	v_add_f32_e64 v163, v107, v109
	v_pk_add_f32 v[164:165], v[110:111], v[112:113]
	v_mfma_f32_32x32x16_bf16 v[18:33], v[200:203], v[146:149], v[18:33]
	v_add_f32_e64 v146, v82, v84
	v_add_f32_e64 v147, v83, v85
	v_add_f32_e64 v148, v86, v88
	v_add_f32_e64 v149, v87, v89
	v_add_f32_e64 v166, v90, v92
	v_add_f32_e64 v167, v91, v93
	v_pk_add_f32 v[168:169], v[94:95], v[96:97]
	v_mfma_f32_32x32x16_bf16 v[50:65], v[158:161], v[150:153], v[50:65]
	v_add_f32_e64 v154, v154, v156
	v_add_f32_e64 v155, v155, v157
	v_add_f32_e64 v156, v162, v164
	v_add_f32_e64 v157, v163, v165
	v_add_f32_e64 v146, v146, v148
	v_add_f32_e64 v147, v147, v149
	v_pk_add_f32 v[148:149], v[166:167], v[168:169]
	v_mfma_f32_32x32x16_bf16 v[18:33], v[204:207], v[150:153], v[18:33]
	v_add_f32_e64 v150, v154, v156
	v_add_f32_e64 v151, v155, v157
	v_add_f32_e64 v146, v146, v148
	v_add_f32_e64 v147, v147, v149
	v_add_f32_e64 v146, v146, v150
	v_add_f32_e64 v147, v147, v151
	v_add_f32_e32 v146, v146, v147
	v_add_f32_e32 v175, v175, v146

.LBB0_333:
	s_lshl_b32 s2, s13, 6
	v_cvt_f32_i32_e32 v2, s2
	v_mov_b32_e32 v179, v178
	v_add_f32_e32 v176, v187, v2
	v_add_f32_e32 v16, 1.0, v176
	v_pk_add_f32 v[2:3], v[176:177], s[14:15] op_sel_hi:[0,1]
	v_pk_add_f32 v[4:5], v[176:177], s[16:17] op_sel_hi:[0,1]
	v_pk_add_f32 v[6:7], v[176:177], s[18:19] op_sel_hi:[0,1]
	v_pk_add_f32 v[8:9], v[176:177], s[20:21] op_sel_hi:[0,1]
	v_pk_add_f32 v[10:11], v[176:177], s[22:23] op_sel_hi:[0,1]
	v_pk_add_f32 v[12:13], v[176:177], s[24:25] op_sel_hi:[0,1]
	v_pk_add_f32 v[14:15], v[176:177], s[26:27] op_sel_hi:[0,1]
	v_and_b32_e32 v3, 0x7fffffff, v3
	v_and_b32_e32 v2, 0x7fffffff, v2
	v_and_b32_e32 v5, 0x7fffffff, v5
	v_and_b32_e32 v4, 0x7fffffff, v4
	v_and_b32_e32 v7, 0x7fffffff, v7
	v_and_b32_e32 v6, 0x7fffffff, v6
	v_and_b32_e32 v9, 0x7fffffff, v9
	v_and_b32_e32 v8, 0x7fffffff, v8
	v_and_b32_e32 v11, 0x7fffffff, v11
	v_and_b32_e32 v10, 0x7fffffff, v10
	v_and_b32_e32 v13, 0x7fffffff, v13
	v_and_b32_e32 v12, 0x7fffffff, v12
	v_and_b32_e32 v15, 0x7fffffff, v15
	v_and_b32_e32 v14, 0x7fffffff, v14
	v_and_b32_e32 v146, 0x7fffffff, v176
	v_and_b32_e32 v147, 0x7fffffff, v16
	v_pk_fma_f32 v[16:17], v[14:15], v[178:179], v[182:183] op_sel_hi:[1,1,0] neg_lo:[0,0,1] neg_hi:[0,0,1]
	v_pk_fma_f32 v[14:15], v[12:13], v[178:179], v[182:183] op_sel_hi:[1,1,0] neg_lo:[0,0,1] neg_hi:[0,0,1]
	v_pk_fma_f32 v[12:13], v[10:11], v[178:179], v[182:183] op_sel_hi:[1,1,0] neg_lo:[0,0,1] neg_hi:[0,0,1]
	v_pk_fma_f32 v[10:11], v[8:9], v[178:179], v[182:183] op_sel_hi:[1,1,0] neg_lo:[0,0,1] neg_hi:[0,0,1]
	v_pk_fma_f32 v[8:9], v[6:7], v[178:179], v[182:183] op_sel_hi:[1,1,0] neg_lo:[0,0,1] neg_hi:[0,0,1]
	v_pk_fma_f32 v[6:7], v[4:5], v[178:179], v[182:183] op_sel_hi:[1,1,0] neg_lo:[0,0,1] neg_hi:[0,0,1]
	v_pk_fma_f32 v[4:5], v[2:3], v[178:179], v[182:183] op_sel_hi:[1,1,0] neg_lo:[0,0,1] neg_hi:[0,0,1]
	v_pk_fma_f32 v[2:3], v[146:147], v[180:181], v[182:183] op_sel_hi:[1,1,0] neg_lo:[0,0,1] neg_hi:[0,0,1]
	s_add_i32 s2, s88, 0x4000
	s_and_b32 s88, s2, 0xffff
	s_cmp_ge_i32 s12, s83
	s_cbranch_scc1 .LBB0_339
.LBB0_334:
	s_add_i32 s2, s88, 0
	v_add_u32_e32 v82, s2, v186
	ds_read_b128 v[162:165], v82
	ds_read_b128 v[150:153], v82 offset:4096
	v_add_u32_e32 v82, s2, v188
	ds_read_b128 v[154:157], v82
	ds_read_b128 v[146:149], v82 offset:4096
	ds_read_b128 v[166:169], v189
	ds_read_b128 v[158:161], v192
	s_cmp_lt_u32 s90, 3
	s_mov_b64 s[2:3], -1
	s_cbranch_scc1 .LBB0_336
	s_cmp_lt_i32 s12, s82
	s_cselect_b64 vcc, -1, 0
	v_cndmask_b32_e32 v82, v197, v196, vcc
	v_pk_add_f32 v[96:97], v[82:83], v[16:17] op_sel_hi:[0,1]
	v_pk_add_f32 v[94:95], v[82:83], v[14:15] op_sel_hi:[0,1]
	v_pk_add_f32 v[92:93], v[82:83], v[12:13] op_sel_hi:[0,1]
	v_pk_add_f32 v[90:91], v[82:83], v[10:11] op_sel_hi:[0,1]
	v_pk_add_f32 v[88:89], v[82:83], v[8:9] op_sel_hi:[0,1]
	v_pk_add_f32 v[86:87], v[82:83], v[6:7] op_sel_hi:[0,1]
	v_pk_add_f32 v[84:85], v[82:83], v[4:5] op_sel_hi:[0,1]
	v_pk_add_f32 v[82:83], v[82:83], v[2:3] op_sel_hi:[0,1]
	s_mov_b64 s[2:3], 0
.LBB0_336:
	s_andn2_b64 vcc, exec, s[2:3]
	s_cbranch_vccnz .LBB0_338
	v_pk_add_f32 v[82:83], v[176:177], s[28:29] op_sel_hi:[0,1]
	v_pk_add_f32 v[84:85], v[176:177], s[30:31] op_sel_hi:[0,1]
	v_pk_add_f32 v[86:87], v[176:177], s[34:35] op_sel_hi:[0,1]
	v_pk_add_f32 v[88:89], v[176:177], s[36:37] op_sel_hi:[0,1]
	v_pk_add_f32 v[90:91], v[176:177], s[38:39] op_sel_hi:[0,1]
	v_pk_add_f32 v[92:93], v[176:177], s[40:41] op_sel_hi:[0,1]
	v_pk_add_f32 v[94:95], v[176:177], s[42:43] op_sel_hi:[0,1]
	v_pk_add_f32 v[96:97], v[176:177], s[44:45] op_sel_hi:[0,1]
	v_and_b32_e32 v99, 0x7fffffff, v97
	v_and_b32_e32 v98, 0x7fffffff, v96
	v_and_b32_e32 v101, 0x7fffffff, v95
	v_and_b32_e32 v100, 0x7fffffff, v94
	v_and_b32_e32 v103, 0x7fffffff, v93
	v_and_b32_e32 v102, 0x7fffffff, v92
	v_and_b32_e32 v105, 0x7fffffff, v91
	v_and_b32_e32 v104, 0x7fffffff, v90
	v_and_b32_e32 v89, 0x7fffffff, v89
	v_and_b32_e32 v88, 0x7fffffff, v88
	v_and_b32_e32 v87, 0x7fffffff, v87
	v_and_b32_e32 v86, 0x7fffffff, v86
	v_and_b32_e32 v85, 0x7fffffff, v85
	v_and_b32_e32 v84, 0x7fffffff, v84
	v_and_b32_e32 v83, 0x7fffffff, v83
	v_and_b32_e32 v82, 0x7fffffff, v82
	v_mov_b32_e32 v179, v178
	v_pk_fma_f32 v[96:97], v[82:83], v[178:179], v[182:183] op_sel_hi:[1,1,0] neg_lo:[0,0,1] neg_hi:[0,0,1]
	v_pk_fma_f32 v[94:95], v[84:85], v[178:179], v[182:183] op_sel_hi:[1,1,0] neg_lo:[0,0,1] neg_hi:[0,0,1]
	v_pk_fma_f32 v[92:93], v[86:87], v[178:179], v[182:183] op_sel_hi:[1,1,0] neg_lo:[0,0,1] neg_hi:[0,0,1]
	v_pk_fma_f32 v[90:91], v[88:89], v[178:179], v[182:183] op_sel_hi:[1,1,0] neg_lo:[0,0,1] neg_hi:[0,0,1]
	v_pk_fma_f32 v[88:89], v[104:105], v[178:179], v[182:183] op_sel_hi:[1,1,0] neg_lo:[0,0,1] neg_hi:[0,0,1]
	v_pk_fma_f32 v[86:87], v[102:103], v[178:179], v[182:183] op_sel_hi:[1,1,0] neg_lo:[0,0,1] neg_hi:[0,0,1]
	v_pk_fma_f32 v[84:85], v[100:101], v[178:179], v[182:183] op_sel_hi:[1,1,0] neg_lo:[0,0,1] neg_hi:[0,0,1]
	v_pk_fma_f32 v[82:83], v[98:99], v[180:181], v[182:183] op_sel_hi:[1,1,0] neg_lo:[0,0,1] neg_hi:[0,0,1]

.LBB0_345:
	ds_read_b64_tr_b16 v[146:147], v199 offset:0
	ds_read_b64_tr_b16 v[148:149], v199 offset:0x200
	ds_read_b64_tr_b16 v[150:151], v199 offset:0x400
	ds_read_b64_tr_b16 v[152:153], v199 offset:0x600
	ds_read_b64_tr_b16 v[154:155], v199 offset:0x800
	ds_read_b64_tr_b16 v[156:157], v199 offset:0xa00
	ds_read_b64_tr_b16 v[158:159], v199 offset:0xc00
	ds_read_b64_tr_b16 v[160:161], v199 offset:0xe00
	ds_read_b64_tr_b16 v[162:163], v199 offset:0x1000
	ds_read_b64_tr_b16 v[164:165], v199 offset:0x1200
	ds_read_b64_tr_b16 v[166:167], v199 offset:0x1400
	ds_read_b64_tr_b16 v[168:169], v199 offset:0x1600
	ds_read_b64_tr_b16 v[200:201], v199 offset:0x1800
	ds_read_b64_tr_b16 v[202:203], v199 offset:0x1a00
	ds_read_b64_tr_b16 v[204:205], v199 offset:0x1c00
	ds_read_b64_tr_b16 v[206:207], v199 offset:0x1e00
	v_exp_f32_e32 v208, v130
	v_exp_f32_e32 v209, v131
	v_exp_f32_e32 v210, v132
	v_exp_f32_e32 v211, v133
	v_exp_f32_e32 v212, v134
	v_exp_f32_e32 v213, v135
	v_exp_f32_e32 v214, v136
	v_exp_f32_e32 v215, v137
	v_exp_f32_e32 v138, v138
	v_exp_f32_e32 v139, v139
	v_exp_f32_e32 v140, v140
	v_exp_f32_e32 v141, v141
	v_exp_f32_e32 v142, v142
	v_exp_f32_e32 v143, v143
	v_exp_f32_e32 v144, v144
	v_exp_f32_e32 v145, v145
	v_cvt_pk_bf16_f32 v130, v208, v209
	v_cvt_pk_bf16_f32 v131, v210, v211
	v_cvt_pk_bf16_f32 v132, v212, v213
	v_cvt_pk_bf16_f32 v133, v214, v215
	v_cvt_pk_bf16_f32 v134, v138, v139
	v_cvt_pk_bf16_f32 v135, v140, v141
	v_cvt_pk_bf16_f32 v136, v142, v143
	v_cvt_pk_bf16_f32 v137, v144, v145
	s_waitcnt lgkmcnt(0)
	s_nop 0
	v_mfma_f32_32x32x16_bf16 v[66:81], v[146:149], v[130:133], v[66:81]
	v_exp_f32_e32 v146, v114
	v_exp_f32_e32 v147, v115
	v_exp_f32_e32 v148, v116
	v_exp_f32_e32 v149, v117
	v_mfma_f32_32x32x16_bf16 v[34:49], v[162:165], v[130:133], v[34:49]
	v_exp_f32_e32 v130, v118
	v_exp_f32_e32 v131, v119
	v_exp_f32_e32 v132, v120
	v_exp_f32_e32 v133, v121
	v_mfma_f32_32x32x16_bf16 v[66:81], v[150:153], v[134:137], v[66:81]
	v_exp_f32_e32 v122, v122
	v_exp_f32_e32 v123, v123
	v_exp_f32_e32 v124, v124
	v_exp_f32_e32 v125, v125
	v_mfma_f32_32x32x16_bf16 v[34:49], v[166:169], v[134:137], v[34:49]
	v_exp_f32_e32 v126, v126
	v_exp_f32_e32 v127, v127
	v_exp_f32_e32 v128, v128
	v_exp_f32_e32 v129, v129
	v_cvt_pk_bf16_f32 v114, v146, v147
	v_cvt_pk_bf16_f32 v115, v148, v149
	v_cvt_pk_bf16_f32 v116, v130, v131
	v_cvt_pk_bf16_f32 v117, v132, v133
	v_cvt_pk_bf16_f32 v118, v122, v123
	v_cvt_pk_bf16_f32 v119, v124, v125
	v_cvt_pk_bf16_f32 v120, v126, v127
	v_cvt_pk_bf16_f32 v121, v128, v129
	s_nop 0
	v_mfma_f32_32x32x16_bf16 v[66:81], v[154:157], v[114:117], v[66:81]
	v_add_f32_e64 v134, v208, v210
	v_add_f32_e64 v135, v209, v211
	v_add_f32_e64 v136, v212, v214
	v_add_f32_e64 v137, v213, v215
	v_add_f32_e64 v138, v138, v140
	v_add_f32_e64 v139, v139, v141
	v_pk_add_f32 v[140:141], v[142:143], v[144:145]
	v_mfma_f32_32x32x16_bf16 v[34:49], v[200:203], v[114:117], v[34:49]
	v_add_f32_e64 v114, v146, v148
	v_add_f32_e64 v115, v147, v149
	v_add_f32_e64 v116, v130, v132
	v_add_f32_e64 v117, v131, v133
	v_add_f32_e64 v122, v122, v124
	v_add_f32_e64 v123, v123, v125
	v_pk_add_f32 v[124:125], v[126:127], v[128:129]
	v_mfma_f32_32x32x16_bf16 v[66:81], v[158:161], v[118:121], v[66:81]
	v_add_f32_e64 v126, v134, v136
	v_add_f32_e64 v127, v135, v137
	v_add_f32_e64 v128, v138, v140
	v_add_f32_e64 v129, v139, v141
	v_add_f32_e64 v114, v114, v116
	v_add_f32_e64 v115, v115, v117
	v_pk_add_f32 v[116:117], v[122:123], v[124:125]
	v_mfma_f32_32x32x16_bf16 v[34:49], v[204:207], v[118:121], v[34:49]
	v_add_f32_e64 v118, v126, v128
	v_add_f32_e64 v119, v127, v129
	v_add_f32_e64 v114, v114, v116
	v_add_f32_e64 v115, v115, v117
	v_add_f32_e64 v114, v114, v118
	v_add_f32_e64 v115, v115, v119
	v_add_f32_e32 v114, v114, v115
	v_add_f32_e32 v174, v174, v114
	s_add_i32 s89, s89, -1
	s_cmp_eq_u32 s86, s12
	s_cbranch_scc1 .LBB0_349

.LBB0_528:
	s_cmp_lt_i32 s86, s78
	s_cselect_b64 s[4:5], -1, 0
	s_add_i32 s12, s84, 0
	v_add_u32_e32 v114, s12, v193
	ds_read_b128 v[158:161], v114
	ds_read_b128 v[150:153], v114 offset:4096
	v_add_u32_e32 v114, s12, v197
	ds_read_b128 v[154:157], v114
	ds_read_b128 v[146:149], v114 offset:4096
	v_add_u32_e32 v114, s52, v193
	v_add_u32_e32 v115, s52, v197
	ds_read_b128 v[166:169], v114
	ds_read_b128 v[162:165], v115
	s_cmp_lt_u32 s86, 4
	s_cselect_b64 s[2:3], -1, 0
	s_mov_b64 s[12:13], -1
	s_and_b64 vcc, exec, s[2:3]
	s_cbranch_vccnz .LBB0_530
	v_cndmask_b32_e64 v114, v196, v195, s[4:5]
	v_pk_add_f32 v[128:129], v[114:115], v[16:17] op_sel_hi:[0,1]
	v_pk_add_f32 v[126:127], v[114:115], v[14:15] op_sel_hi:[0,1]
	v_pk_add_f32 v[124:125], v[114:115], v[12:13] op_sel_hi:[0,1]
	v_pk_add_f32 v[122:123], v[114:115], v[10:11] op_sel_hi:[0,1]
	v_pk_add_f32 v[120:121], v[114:115], v[8:9] op_sel_hi:[0,1]
	v_pk_add_f32 v[118:119], v[114:115], v[6:7] op_sel_hi:[0,1]
	v_pk_add_f32 v[116:117], v[114:115], v[4:5] op_sel_hi:[0,1]
	v_pk_add_f32 v[114:115], v[114:115], v[2:3] op_sel_hi:[0,1]
	s_mov_b64 s[12:13], 0

.LBB0_537:
	s_and_b64 vcc, exec, s[76:77]
	v_add_u32_e32 v198, s84, v194
	s_cbranch_vccz .LBB0_539
	ds_read_b64_tr_b16 v[146:147], v198 offset:0
	ds_read_b64_tr_b16 v[148:149], v198 offset:0x200
	ds_read_b64_tr_b16 v[150:151], v198 offset:0x400
	ds_read_b64_tr_b16 v[152:153], v198 offset:0x600
	ds_read_b64_tr_b16 v[154:155], v198 offset:0x800
	ds_read_b64_tr_b16 v[156:157], v198 offset:0xa00
	ds_read_b64_tr_b16 v[158:159], v198 offset:0xc00
	ds_read_b64_tr_b16 v[160:161], v198 offset:0xe00
	ds_read_b64_tr_b16 v[162:163], v198 offset:0x1000
	ds_read_b64_tr_b16 v[164:165], v198 offset:0x1200
	ds_read_b64_tr_b16 v[166:167], v198 offset:0x1400
	ds_read_b64_tr_b16 v[168:169], v198 offset:0x1600
	ds_read_b64_tr_b16 v[200:201], v198 offset:0x1800
	ds_read_b64_tr_b16 v[202:203], v198 offset:0x1a00
	ds_read_b64_tr_b16 v[204:205], v198 offset:0x1c00
	ds_read_b64_tr_b16 v[206:207], v198 offset:0x1e00
	v_exp_f32_e32 v98, v98
	v_exp_f32_e32 v99, v99
	v_exp_f32_e32 v100, v100
	v_exp_f32_e32 v101, v101
	v_exp_f32_e32 v102, v102
	v_exp_f32_e32 v103, v103
	v_exp_f32_e32 v104, v104
	v_exp_f32_e32 v105, v105
	v_exp_f32_e32 v106, v106
	v_exp_f32_e32 v107, v107
	v_exp_f32_e32 v108, v108
	v_exp_f32_e32 v109, v109
	v_exp_f32_e32 v110, v110
	v_exp_f32_e32 v111, v111
	v_exp_f32_e32 v112, v112
	v_exp_f32_e32 v113, v113
	v_cvt_pk_bf16_f32 v208, v98, v99
	v_cvt_pk_bf16_f32 v209, v100, v101
	v_cvt_pk_bf16_f32 v210, v102, v103
	v_cvt_pk_bf16_f32 v211, v104, v105
	v_cvt_pk_bf16_f32 v212, v106, v107
	v_cvt_pk_bf16_f32 v213, v108, v109
	v_cvt_pk_bf16_f32 v214, v110, v111
	v_cvt_pk_bf16_f32 v215, v112, v113
	s_waitcnt lgkmcnt(0)
	s_nop 0
	v_mfma_f32_32x32x16_bf16 v[50:65], v[146:149], v[208:211], v[50:65]
	v_exp_f32_e32 v82, v82
	v_exp_f32_e32 v83, v83
	v_exp_f32_e32 v84, v84
	v_exp_f32_e32 v85, v85
	v_mfma_f32_32x32x16_bf16 v[18:33], v[162:165], v[208:211], v[18:33]
	v_exp_f32_e32 v86, v86
	v_exp_f32_e32 v87, v87
	v_exp_f32_e32 v88, v88
	v_exp_f32_e32 v89, v89
	v_mfma_f32_32x32x16_bf16 v[50:65], v[150:153], v[212:215], v[50:65]
	v_exp_f32_e32 v90, v90
	v_exp_f32_e32 v91, v91
	v_exp_f32_e32 v92, v92
	v_exp_f32_e32 v93, v93
	v_mfma_f32_32x32x16_bf16 v[18:33], v[166:169], v[212:215], v[18:33]
	v_exp_f32_e32 v94, v94
	v_exp_f32_e32 v95, v95
	v_exp_f32_e32 v96, v96
	v_exp_f32_e32 v97, v97
	v_cvt_pk_bf16_f32 v146, v82, v83
	v_cvt_pk_bf16_f32 v147, v84, v85
	v_cvt_pk_bf16_f32 v148, v86, v87
	v_cvt_pk_bf16_f32 v149, v88, v89
	v_cvt_pk_bf16_f32 v150, v90, v91
	v_cvt_pk_bf16_f32 v151, v92, v93
	v_cvt_pk_bf16_f32 v152, v94, v95
	v_cvt_pk_bf16_f32 v153, v96, v97
	s_nop 0
	v_mfma_f32_32x32x16_bf16 v[50:65], v[154:157], v[146:149], v[50:65]
	v_add_f32_e64 v154, v98, v100
	v_add_f32_e64 v155, v99, v101
	v_add_f32_e64 v156, v102, v104
	v_add_f32_e64 v157, v103, v105
	v_add_f32_e64 v162, v106, v108
	v_add_f32_e64 v163, v107, v109
	v_pk_add_f32 v[164:165], v[110:111], v[112:113]
	v_mfma_f32_32x32x16_bf16 v[18:33], v[200:203], v[146:149], v[18:33]
	v_add_f32_e64 v146, v82, v84
	v_add_f32_e64 v147, v83, v85
	v_add_f32_e64 v148, v86, v88
	v_add_f32_e64 v149, v87, v89
	v_add_f32_e64 v166, v90, v92
	v_add_f32_e64 v167, v91, v93
	v_pk_add_f32 v[168:169], v[94:95], v[96:97]
	v_mfma_f32_32x32x16_bf16 v[50:65], v[158:161], v[150:153], v[50:65]
	v_add_f32_e64 v154, v154, v156
	v_add_f32_e64 v155, v155, v157
	v_add_f32_e64 v156, v162, v164
	v_add_f32_e64 v157, v163, v165
	v_add_f32_e64 v146, v146, v148
	v_add_f32_e64 v147, v147, v149
	v_pk_add_f32 v[148:149], v[166:167], v[168:169]
	v_mfma_f32_32x32x16_bf16 v[18:33], v[204:207], v[150:153], v[18:33]
	v_add_f32_e64 v150, v154, v156
	v_add_f32_e64 v151, v155, v157
	v_add_f32_e64 v146, v146, v148
	v_add_f32_e64 v147, v147, v149
	v_add_f32_e64 v146, v146, v150
	v_add_f32_e64 v147, v147, v151
	v_add_f32_e32 v146, v146, v147
	v_add_f32_e32 v175, v175, v146

.LBB0_551:
	s_lshl_b32 s2, s13, 6
	v_cvt_f32_i32_e32 v2, s2
	v_mov_b32_e32 v179, v178
	v_add_f32_e32 v176, v185, v2
	v_add_f32_e32 v16, 1.0, v176
	v_pk_add_f32 v[2:3], v[176:177], s[14:15] op_sel_hi:[0,1]
	v_pk_add_f32 v[4:5], v[176:177], s[16:17] op_sel_hi:[0,1]
	v_pk_add_f32 v[6:7], v[176:177], s[18:19] op_sel_hi:[0,1]
	v_pk_add_f32 v[8:9], v[176:177], s[20:21] op_sel_hi:[0,1]
	v_pk_add_f32 v[10:11], v[176:177], s[22:23] op_sel_hi:[0,1]
	v_pk_add_f32 v[12:13], v[176:177], s[24:25] op_sel_hi:[0,1]
	v_pk_add_f32 v[14:15], v[176:177], s[26:27] op_sel_hi:[0,1]
	v_and_b32_e32 v3, 0x7fffffff, v3
	v_and_b32_e32 v2, 0x7fffffff, v2
	v_and_b32_e32 v5, 0x7fffffff, v5
	v_and_b32_e32 v4, 0x7fffffff, v4
	v_and_b32_e32 v7, 0x7fffffff, v7
	v_and_b32_e32 v6, 0x7fffffff, v6
	v_and_b32_e32 v9, 0x7fffffff, v9
	v_and_b32_e32 v8, 0x7fffffff, v8
	v_and_b32_e32 v11, 0x7fffffff, v11
	v_and_b32_e32 v10, 0x7fffffff, v10
	v_and_b32_e32 v13, 0x7fffffff, v13
	v_and_b32_e32 v12, 0x7fffffff, v12
	v_and_b32_e32 v15, 0x7fffffff, v15
	v_and_b32_e32 v14, 0x7fffffff, v14
	v_and_b32_e32 v146, 0x7fffffff, v176
	v_and_b32_e32 v147, 0x7fffffff, v16
	v_pk_fma_f32 v[16:17], v[14:15], v[178:179], v[182:183] op_sel_hi:[1,1,0] neg_lo:[0,0,1] neg_hi:[0,0,1]
	v_pk_fma_f32 v[14:15], v[12:13], v[178:179], v[182:183] op_sel_hi:[1,1,0] neg_lo:[0,0,1] neg_hi:[0,0,1]
	v_pk_fma_f32 v[12:13], v[10:11], v[178:179], v[182:183] op_sel_hi:[1,1,0] neg_lo:[0,0,1] neg_hi:[0,0,1]
	v_pk_fma_f32 v[10:11], v[8:9], v[178:179], v[182:183] op_sel_hi:[1,1,0] neg_lo:[0,0,1] neg_hi:[0,0,1]
	v_pk_fma_f32 v[8:9], v[6:7], v[178:179], v[182:183] op_sel_hi:[1,1,0] neg_lo:[0,0,1] neg_hi:[0,0,1]
	v_pk_fma_f32 v[6:7], v[4:5], v[178:179], v[182:183] op_sel_hi:[1,1,0] neg_lo:[0,0,1] neg_hi:[0,0,1]
	v_pk_fma_f32 v[4:5], v[2:3], v[178:179], v[182:183] op_sel_hi:[1,1,0] neg_lo:[0,0,1] neg_hi:[0,0,1]
	v_pk_fma_f32 v[2:3], v[146:147], v[180:181], v[182:183] op_sel_hi:[1,1,0] neg_lo:[0,0,1] neg_hi:[0,0,1]
	s_add_i32 s2, s84, 0x4000
	s_and_b32 s84, s2, 0xffff
	s_cmp_ge_i32 s12, s79
	s_cbranch_scc1 .LBB0_557
.LBB0_552:
	s_add_i32 s2, s84, 0
	v_add_u32_e32 v82, s2, v173
	ds_read_b128 v[162:165], v82
	ds_read_b128 v[150:153], v82 offset:4096
	v_add_u32_e32 v82, s2, v187
	ds_read_b128 v[154:157], v82
	ds_read_b128 v[146:149], v82 offset:4096
	ds_read_b128 v[166:169], v188
	ds_read_b128 v[158:161], v189
	s_cmp_lt_u32 s86, 3
	s_mov_b64 s[2:3], -1
	s_cbranch_scc1 .LBB0_554
	s_cmp_lt_i32 s12, s78
	s_cselect_b64 vcc, -1, 0
	v_cndmask_b32_e32 v82, v196, v195, vcc
	v_pk_add_f32 v[96:97], v[82:83], v[16:17] op_sel_hi:[0,1]
	v_pk_add_f32 v[94:95], v[82:83], v[14:15] op_sel_hi:[0,1]
	v_pk_add_f32 v[92:93], v[82:83], v[12:13] op_sel_hi:[0,1]
	v_pk_add_f32 v[90:91], v[82:83], v[10:11] op_sel_hi:[0,1]
	v_pk_add_f32 v[88:89], v[82:83], v[8:9] op_sel_hi:[0,1]
	v_pk_add_f32 v[86:87], v[82:83], v[6:7] op_sel_hi:[0,1]
	v_pk_add_f32 v[84:85], v[82:83], v[4:5] op_sel_hi:[0,1]
	v_pk_add_f32 v[82:83], v[82:83], v[2:3] op_sel_hi:[0,1]
	s_mov_b64 s[2:3], 0

.LBB0_563:
	ds_read_b64_tr_b16 v[146:147], v198 offset:0
	ds_read_b64_tr_b16 v[148:149], v198 offset:0x200
	ds_read_b64_tr_b16 v[150:151], v198 offset:0x400
	ds_read_b64_tr_b16 v[152:153], v198 offset:0x600
	ds_read_b64_tr_b16 v[154:155], v198 offset:0x800
	ds_read_b64_tr_b16 v[156:157], v198 offset:0xa00
	ds_read_b64_tr_b16 v[158:159], v198 offset:0xc00
	ds_read_b64_tr_b16 v[160:161], v198 offset:0xe00
	ds_read_b64_tr_b16 v[162:163], v198 offset:0x1000
	ds_read_b64_tr_b16 v[164:165], v198 offset:0x1200
	ds_read_b64_tr_b16 v[166:167], v198 offset:0x1400
	ds_read_b64_tr_b16 v[168:169], v198 offset:0x1600
	ds_read_b64_tr_b16 v[200:201], v198 offset:0x1800
	ds_read_b64_tr_b16 v[202:203], v198 offset:0x1a00
	ds_read_b64_tr_b16 v[204:205], v198 offset:0x1c00
	ds_read_b64_tr_b16 v[206:207], v198 offset:0x1e00
	v_exp_f32_e32 v198, v130
	v_exp_f32_e32 v199, v131
	v_exp_f32_e32 v208, v132
	v_exp_f32_e32 v209, v133
	v_exp_f32_e32 v210, v134
	v_exp_f32_e32 v211, v135
	v_exp_f32_e32 v212, v136
	v_exp_f32_e32 v213, v137
	v_exp_f32_e32 v138, v138
	v_exp_f32_e32 v139, v139
	v_exp_f32_e32 v140, v140
	v_exp_f32_e32 v141, v141
	v_exp_f32_e32 v142, v142
	v_exp_f32_e32 v143, v143
	v_exp_f32_e32 v144, v144
	v_exp_f32_e32 v145, v145
	v_cvt_pk_bf16_f32 v130, v198, v199
	v_cvt_pk_bf16_f32 v131, v208, v209
	v_cvt_pk_bf16_f32 v132, v210, v211
	v_cvt_pk_bf16_f32 v133, v212, v213
	v_cvt_pk_bf16_f32 v134, v138, v139
	v_cvt_pk_bf16_f32 v135, v140, v141
	v_cvt_pk_bf16_f32 v136, v142, v143
	v_cvt_pk_bf16_f32 v137, v144, v145
	s_waitcnt lgkmcnt(0)
	s_nop 0
	v_mfma_f32_32x32x16_bf16 v[66:81], v[146:149], v[130:133], v[66:81]
	v_exp_f32_e32 v146, v114
	v_exp_f32_e32 v147, v115
	v_exp_f32_e32 v148, v116
	v_exp_f32_e32 v149, v117
	v_mfma_f32_32x32x16_bf16 v[34:49], v[162:165], v[130:133], v[34:49]
	v_exp_f32_e32 v130, v118
	v_exp_f32_e32 v131, v119
	v_exp_f32_e32 v132, v120
	v_exp_f32_e32 v133, v121
	v_mfma_f32_32x32x16_bf16 v[66:81], v[150:153], v[134:137], v[66:81]
	v_exp_f32_e32 v122, v122
	v_exp_f32_e32 v123, v123
	v_exp_f32_e32 v124, v124
	v_exp_f32_e32 v125, v125
	v_mfma_f32_32x32x16_bf16 v[34:49], v[166:169], v[134:137], v[34:49]
	v_exp_f32_e32 v126, v126
	v_exp_f32_e32 v127, v127
	v_exp_f32_e32 v128, v128
	v_exp_f32_e32 v129, v129
	v_cvt_pk_bf16_f32 v114, v146, v147
	v_cvt_pk_bf16_f32 v115, v148, v149
	v_cvt_pk_bf16_f32 v116, v130, v131
	v_cvt_pk_bf16_f32 v117, v132, v133
	v_cvt_pk_bf16_f32 v118, v122, v123
	v_cvt_pk_bf16_f32 v119, v124, v125
	v_cvt_pk_bf16_f32 v120, v126, v127
	v_cvt_pk_bf16_f32 v121, v128, v129
	s_nop 0
	v_mfma_f32_32x32x16_bf16 v[66:81], v[154:157], v[114:117], v[66:81]
	v_add_f32_e64 v134, v198, v208
	v_add_f32_e64 v135, v199, v209
	v_add_f32_e64 v136, v210, v212
	v_add_f32_e64 v137, v211, v213
	v_add_f32_e64 v138, v138, v140
	v_add_f32_e64 v139, v139, v141
	v_pk_add_f32 v[140:141], v[142:143], v[144:145]
	v_mfma_f32_32x32x16_bf16 v[34:49], v[200:203], v[114:117], v[34:49]
	v_add_f32_e64 v114, v146, v148
	v_add_f32_e64 v115, v147, v149
	v_add_f32_e64 v116, v130, v132
	v_add_f32_e64 v117, v131, v133
	v_add_f32_e64 v122, v122, v124
	v_add_f32_e64 v123, v123, v125
	v_pk_add_f32 v[124:125], v[126:127], v[128:129]
	v_mfma_f32_32x32x16_bf16 v[66:81], v[158:161], v[118:121], v[66:81]
	v_add_f32_e64 v126, v134, v136
	v_add_f32_e64 v127, v135, v137
	v_add_f32_e64 v128, v138, v140
	v_add_f32_e64 v129, v139, v141
	v_add_f32_e64 v114, v114, v116
	v_add_f32_e64 v115, v115, v117
	v_pk_add_f32 v[116:117], v[122:123], v[124:125]
	v_mfma_f32_32x32x16_bf16 v[34:49], v[204:207], v[118:121], v[34:49]
	v_add_f32_e64 v118, v126, v128
	v_add_f32_e64 v119, v127, v129
	v_add_f32_e64 v114, v114, v116
	v_add_f32_e64 v115, v115, v117
	v_add_f32_e64 v114, v114, v118
	v_add_f32_e64 v115, v115, v119
	v_add_f32_e32 v114, v114, v115
	v_add_f32_e32 v174, v174, v114
	s_add_i32 s85, s85, -1
	s_cmp_eq_u32 s82, s12
	s_cbranch_scc1 .LBB0_569

	.amdhsa_kernel _Z14fwd_megakernel4Args
		.amdhsa_group_segment_fixed_size 0
		.amdhsa_private_segment_fixed_size 0
		.amdhsa_kernarg_size 392
		.amdhsa_user_sgpr_count 2
		.amdhsa_user_sgpr_dispatch_ptr 0
		.amdhsa_user_sgpr_queue_ptr 0
		.amdhsa_user_sgpr_kernarg_segment_ptr 1
		.amdhsa_user_sgpr_dispatch_id 0
		.amdhsa_user_sgpr_kernarg_preload_length 0
		.amdhsa_user_sgpr_kernarg_preload_offset 0
		.amdhsa_user_sgpr_private_segment_size 0
		.amdhsa_uses_dynamic_stack 0
		.amdhsa_enable_private_segment 0
		.amdhsa_system_sgpr_workgroup_id_x 1
		.amdhsa_system_sgpr_workgroup_id_y 0
		.amdhsa_system_sgpr_workgroup_id_z 0
		.amdhsa_system_sgpr_workgroup_info 0
		.amdhsa_system_vgpr_workitem_id 2
		.amdhsa_next_free_vgpr 254
		.amdhsa_next_free_sgpr 102
		.amdhsa_accum_offset 256
		.amdhsa_reserve_vcc 1
		.amdhsa_float_round_mode_32 0
		.amdhsa_float_round_mode_16_64 0
		.amdhsa_float_denorm_mode_32 3
		.amdhsa_float_denorm_mode_16_64 3
		.amdhsa_dx10_clamp 1
		.amdhsa_ieee_mode 1
		.amdhsa_fp16_overflow 0
		.amdhsa_tg_split 0
		.amdhsa_exception_fp_ieee_invalid_op 0
		.amdhsa_exception_fp_denorm_src 0
		.amdhsa_exception_fp_ieee_div_zero 0
		.amdhsa_exception_fp_ieee_overflow 0
		.amdhsa_exception_fp_ieee_underflow 0
		.amdhsa_exception_fp_ieee_inexact 0
		.amdhsa_exception_int_div_zero 0
	.end_amdhsa_kernel

amdhsa.kernels:
  - .agpr_count:     0
    .args:
      - .offset:         0
        .size:           136
        .value_kind:     by_value
      - .offset:         136
        .size:           4
        .value_kind:     hidden_block_count_x
      - .offset:         140
        .size:           4
        .value_kind:     hidden_block_count_y
      - .offset:         144
        .size:           4
        .value_kind:     hidden_block_count_z
      - .offset:         148
        .size:           2
        .value_kind:     hidden_group_size_x
      - .offset:         150
        .size:           2
        .value_kind:     hidden_group_size_y
      - .offset:         152
        .size:           2
        .value_kind:     hidden_group_size_z
      - .offset:         154
        .size:           2
        .value_kind:     hidden_remainder_x
      - .offset:         156
        .size:           2
        .value_kind:     hidden_remainder_y
      - .offset:         158
        .size:           2
        .value_kind:     hidden_remainder_z
      - .offset:         176
        .size:           8
        .value_kind:     hidden_global_offset_x
      - .offset:         184
        .size:           8
        .value_kind:     hidden_global_offset_y
      - .offset:         192
        .size:           8
        .value_kind:     hidden_global_offset_z
      - .offset:         200
        .size:           2
        .value_kind:     hidden_grid_dims
      - .offset:         224
        .size:           8
        .value_kind:     hidden_multigrid_sync_arg
      - .offset:         256
        .size:           4
        .value_kind:     hidden_dynamic_lds_size
    .group_segment_fixed_size: 0
    .kernarg_segment_align: 8
    .kernarg_segment_size: 392
    .language:       OpenCL C
    .language_version:
      - 2
      - 0
    .max_flat_workgroup_size: 512
    .name:           _Z14fwd_megakernel4Args
    .private_segment_fixed_size: 0
    .sgpr_count:     108
    .sgpr_spill_count: 98
    .symbol:         _Z14fwd_megakernel4Args.kd
    .uniform_work_group_size: 1
    .uses_dynamic_stack: false
    .vgpr_count:     254
    .vgpr_spill_count: 0
    .wavefront_size: 64
